# v62 + ai=1 half of the split epilogue spread over the next unit's first two load segments (4 + 4 stores)
# baseline (speedup 1.0000x reference)
; __device__ __forceinline__ unsigned cvt_pk_bf16(float lo, float hi) { const f32x2_t v = {lo, hi}; const bf16x2_t c = __builtin_convertvector(v, bf16x2_t); return __builtin_bit_cast(unsigned, c); }
; #define PG8_STAGE(bufoff, gbase, voff) do { _Pragma("unroll") for (int _i = 0; _i < 2; ++_i) \
;         __builtin_amdgcn_global_load_lds((const unsigned*)((const char*)(gbase) + (voff)[_i]), (PG8_LAS unsigned*)(lds + (bufoff) + ldsw + _i * 8192), 16, 0, 0); } while (0)
; #define PG8_LDA(dst, b, h) do { _Pragma("unroll") for (int m = 0; m < 4; ++m) _Pragma("unroll") for (int k = 0; k < 2; ++k) dst[m][k] = *(const PG8_LAS bf16x8*)(lds + PG8_SA(b, h) + aoff + m * 2048 + k * 1024); } while (0)
; #define PG8_BAR __builtin_amdgcn_s_barrier()
;     __device__ __forceinline__ void operator()(const f32x4 (&acc)[2][2][4][2], const Unit& u, int wr, int wc, int fr, int fq) const {
;     ...
;         for (int ai = 0; ai < 2; ++ai)
; #pragma unroll
;             for (int m = 0; m < 4; ++m) { bf16_t* rowp = O + (size_t)(row0 + ai * HALF + m * 16) * ldc + col0;
; #pragma unroll
;                 for (int bj = 0; bj < 2; ++bj) { const f32x4 v0 = acc[ai][bj][m][0], v1 = acc[ai][bj][m][1];
;                     u32x4 w; w.x = cvt_pk_bf16(v0[0], v0[1]); w.y = cvt_pk_bf16(v0[2], v0[3]); w.z = cvt_pk_bf16(v1[0], v1[1]); w.w = cvt_pk_bf16(v1[2], v1[3]);
;                     *(u32x4*)(rowp + bj * HALF) = w; } }
; template <class Epi, class Sched, bool ALIGN_EPI = false, bool SP2 = false, bool KHOOK = false>
; __device__ __forceinline__ void gemm_phase(PG8_LAS unsigned char* lds, const Gemm g, const Sched& S, const Epi& E, const int tid_in) {
;     ...
;             PG8_LDB(B0, 0, 0); PG8_LDB(B1, 0, 1); PG8_SCHED; PG8_LDA(At, 0, 0); PG8_STAGE(PG8_SA(1, 1), a1 + hstep, voffA);
;             PG8_WAIT_V(8); PG8_WAIT_L(0); PG8_BAR; PG8_MMA(0, 0, At, B0); PG8_MMA(0, 1, At, B1); PG8_BAR; PG8_SCHED;
;             PG8_LDA(At, 0, 1); PG8_STAGE(PG8_SB(0, 0), b2, voffB); PG8_STAGE(PG8_SB(0, 1), b2 + hstep, voffB); PG8_STAGE(PG8_SA(0, 0), a2, voffA);
;             PG8_WAIT_V(8); PG8_WAIT_L(0); PG8_BAR; PG8_MMA(1, 0, At, B0); PG8_MMA(1, 1, At, B1); PG8_BAR; PG8_SCHED;
;             PG8_LDB(B0, 1, 0); PG8_LDB(B1, 1, 1); PG8_SCHED; PG8_LDA(At, 1, 0); PG8_STAGE(PG8_SA(0, 1), a2 + hstep, voffA);
;             PG8_WAIT_V(8); PG8_WAIT_L(0); PG8_BAR; PG8_MMA(0, 0, At, B0); PG8_MMA(0, 1, At, B1); PG8_BAR; PG8_SCHED;
.Lg1_peel_e1:
	s_add_u32 s45, s48, 0xfff80080
	s_addc_u32 s46, s49, -1
	s_add_i32 s47, 0, 0x10000
	s_cmp_eq_u32 s44, 28
	s_cselect_b32 s57, s11, s46
	s_cselect_b32 s56, s17, s45
	s_cselect_b32 s53, s15, s42
	s_cselect_b32 s52, s18, s19
	s_add_i32 s45, 0, 0x14000
	v_add_u32_e32 v156, s47, v141
	v_add_u32_e32 v172, s45, v141
	ds_read_b128 v[144:147], v156
	ds_read_b128 v[148:151], v156 offset:1024
	ds_read_b128 v[152:155], v156 offset:2048
	ds_read_b128 v[156:159], v156 offset:3072
	ds_read_b128 v[160:163], v172
	ds_read_b128 v[164:167], v172 offset:1024
	ds_read_b128 v[168:171], v172 offset:2048
	ds_read_b128 v[172:175], v172 offset:3072
	v_lshl_add_u64 v[192:193], s[48:49], 0, v[136:137]
	s_add_i32 m0, s13, 0xc000
	ds_read_b128 v[176:179], v143
	ds_read_b128 v[180:183], v143 offset:1024
	ds_read_b128 v[184:187], v143 offset:2048
	ds_read_b128 v[188:191], v143 offset:3072
	ds_read_b128 v[198:201], v143 offset:4096
	ds_read_b128 v[202:205], v143 offset:5120
	ds_read_b128 v[206:209], v143 offset:6144
	ds_read_b128 v[210:213], v143 offset:7168
	global_load_lds_dwordx4 v[192:193], off
	v_lshl_add_u64 v[192:193], s[48:49], 0, v[138:139]
	s_add_i32 m0, s13, 0xe000
	s_nop 0
	global_load_lds_dwordx4 v[192:193], off
	v_lshl_add_u32 v246, s68, 8, v140
	v_add_u32_e32 v246, 0x80, v246
	v_lshl_or_b32 v222, s69, 8, v142
	v_lshlrev_b32_e32 v222, 1, v222
	v_mov_b32_e32 v223, 0
	v_mad_u64_u32 v[248:249], s[70:71], v246, s67, v[222:223]
	s_mov_b32 s72, 0xa2000
	s_mov_b32 s73, 0
	v_lshl_add_u64 v[248:249], v[248:249], 0, s[76:77]
	v_cvt_pk_bf16_f32 v62, v62, v63
	v_cvt_pk_bf16_f32 v63, v64, v65
	v_cvt_pk_bf16_f32 v64, v58, v59
	v_cvt_pk_bf16_f32 v65, v60, v61
	global_store_dwordx4 v[248:249], v[62:65], off
	v_cvt_pk_bf16_f32 v46, v46, v47
	v_cvt_pk_bf16_f32 v47, v48, v49
	v_cvt_pk_bf16_f32 v48, v42, v43
	v_cvt_pk_bf16_f32 v49, v44, v45
	global_store_dwordx4 v[248:249], v[46:49], off offset:256
	v_lshl_add_u64 v[248:249], v[248:249], 0, s[72:73]
	v_cvt_pk_bf16_f32 v54, v54, v55
	v_cvt_pk_bf16_f32 v55, v56, v57
	v_cvt_pk_bf16_f32 v56, v50, v51
	v_cvt_pk_bf16_f32 v57, v52, v53
	global_store_dwordx4 v[248:249], v[54:57], off
	v_cvt_pk_bf16_f32 v28, v28, v29
	v_cvt_pk_bf16_f32 v29, v30, v31
	v_cvt_pk_bf16_f32 v30, v24, v25
	v_cvt_pk_bf16_f32 v31, v26, v27
	global_store_dwordx4 v[248:249], v[28:31], off offset:256
	s_waitcnt vmcnt(20)
	s_waitcnt lgkmcnt(0)
	s_barrier
	s_setprio 1
	s_waitcnt lgkmcnt(0)
	v_mfma_f32_16x16x32_bf16 v[126:129], v[144:147], v[176:179], 0
	v_mfma_f32_16x16x32_bf16 v[122:125], v[152:155], v[176:179], 0
	v_mfma_f32_16x16x32_bf16 v[118:121], v[144:147], v[184:187], 0
	v_mfma_f32_16x16x32_bf16 v[114:117], v[152:155], v[184:187], 0
	v_mfma_f32_16x16x32_bf16 v[102:105], v[144:147], v[198:201], 0
	v_mfma_f32_16x16x32_bf16 v[98:101], v[152:155], v[198:201], 0
	v_mfma_f32_16x16x32_bf16 v[86:89], v[144:147], v[206:209], 0
	v_mfma_f32_16x16x32_bf16 v[82:85], v[152:155], v[206:209], 0
	v_mfma_f32_16x16x32_bf16 v[126:129], v[148:151], v[180:183], v[126:129]
	v_mfma_f32_16x16x32_bf16 v[122:125], v[156:159], v[180:183], v[122:125]
	v_mfma_f32_16x16x32_bf16 v[118:121], v[148:151], v[188:191], v[118:121]
	v_mfma_f32_16x16x32_bf16 v[114:117], v[156:159], v[188:191], v[114:117]
	v_mfma_f32_16x16x32_bf16 v[102:105], v[148:151], v[202:205], v[102:105]
	v_mfma_f32_16x16x32_bf16 v[98:101], v[156:159], v[202:205], v[98:101]
	v_mfma_f32_16x16x32_bf16 v[86:89], v[148:151], v[210:213], v[86:89]
	v_mfma_f32_16x16x32_bf16 v[82:85], v[156:159], v[210:213], v[82:85]
	s_setprio 0
	s_setprio 1
	v_mfma_f32_16x16x32_bf16 v[110:113], v[160:163], v[176:179], 0
	v_mfma_f32_16x16x32_bf16 v[106:109], v[168:171], v[176:179], 0
	v_mfma_f32_16x16x32_bf16 v[94:97], v[160:163], v[184:187], 0
	v_mfma_f32_16x16x32_bf16 v[90:93], v[168:171], v[184:187], 0
	v_mfma_f32_16x16x32_bf16 v[78:81], v[160:163], v[198:201], 0
	v_mfma_f32_16x16x32_bf16 v[74:77], v[168:171], v[198:201], 0
	v_mfma_f32_16x16x32_bf16 v[70:73], v[160:163], v[206:209], 0
	v_mfma_f32_16x16x32_bf16 v[66:69], v[168:171], v[206:209], 0
	v_mfma_f32_16x16x32_bf16 v[110:113], v[164:167], v[180:183], v[110:113]
	v_mfma_f32_16x16x32_bf16 v[106:109], v[172:175], v[180:183], v[106:109]
	v_mfma_f32_16x16x32_bf16 v[94:97], v[164:167], v[188:191], v[94:97]
	v_mfma_f32_16x16x32_bf16 v[90:93], v[172:175], v[188:191], v[90:93]
	v_mfma_f32_16x16x32_bf16 v[78:81], v[164:167], v[202:205], v[78:81]
	v_mfma_f32_16x16x32_bf16 v[74:77], v[172:175], v[202:205], v[74:77]
	v_mfma_f32_16x16x32_bf16 v[70:73], v[164:167], v[210:213], v[70:73]
	v_mfma_f32_16x16x32_bf16 v[66:69], v[172:175], v[210:213], v[66:69]
	s_setprio 0
	s_barrier
	s_add_i32 s46, s47, s37
	v_lshl_add_u64 v[192:193], s[52:53], 0, v[32:33]
	s_mov_b32 m0, s46
	ds_read_b128 v[176:179], v143 offset:16384
	ds_read_b128 v[180:183], v143 offset:17408
	ds_read_b128 v[184:187], v143 offset:18432
	ds_read_b128 v[188:191], v143 offset:19456
	ds_read_b128 v[198:201], v143 offset:20480
	ds_read_b128 v[202:205], v143 offset:21504
	ds_read_b128 v[206:209], v143 offset:22528
	ds_read_b128 v[210:213], v143 offset:23552
	global_load_lds_dwordx4 v[192:193], off
	s_add_i32 m0, s46, 0x2000
	s_add_u32 s46, s52, 0x80000
	v_lshl_add_u64 v[214:215], s[52:53], 0, v[134:135]
	s_addc_u32 s47, s53, 0
	s_add_i32 s45, s45, s37
	global_load_lds_dwordx4 v[214:215], off
	v_lshl_add_u64 v[216:217], s[46:47], 0, v[32:33]
	s_mov_b32 m0, s45
	v_lshl_add_u64 v[218:219], s[56:57], 0, v[132:133]
	global_load_lds_dwordx4 v[216:217], off
	v_lshl_add_u64 v[216:217], s[46:47], 0, v[134:135]
	s_add_i32 m0, s45, 0x2000
	s_nop 0
	global_load_lds_dwordx4 v[216:217], off
	v_lshl_add_u64 v[216:217], s[56:57], 0, v[130:131]
	s_mov_b32 m0, s13
	s_nop 0
	global_load_lds_dwordx4 v[216:217], off
	s_mov_b32 m0, s24
	s_nop 0
	global_load_lds_dwordx4 v[218:219], off
	v_lshl_add_u64 v[248:249], v[248:249], 0, s[72:73]
	v_cvt_pk_bf16_f32 v38, v38, v39
	v_cvt_pk_bf16_f32 v39, v40, v41
	v_cvt_pk_bf16_f32 v40, v34, v35
	v_cvt_pk_bf16_f32 v41, v36, v37
	global_store_dwordx4 v[248:249], v[38:41], off
	v_cvt_pk_bf16_f32 v12, v12, v13
	v_cvt_pk_bf16_f32 v13, v14, v15
	v_cvt_pk_bf16_f32 v14, v8, v9
	v_cvt_pk_bf16_f32 v15, v10, v11
	global_store_dwordx4 v[248:249], v[12:15], off offset:256
	v_lshl_add_u64 v[248:249], v[248:249], 0, s[72:73]
	v_cvt_pk_bf16_f32 v20, v20, v21
	v_cvt_pk_bf16_f32 v21, v22, v23
	v_cvt_pk_bf16_f32 v22, v16, v17
	v_cvt_pk_bf16_f32 v23, v18, v19
	global_store_dwordx4 v[248:249], v[20:23], off
	v_cvt_pk_bf16_f32 v4, v4, v5
	v_cvt_pk_bf16_f32 v5, v6, v7
	v_cvt_pk_bf16_f32 v6, v0, v1
	v_cvt_pk_bf16_f32 v7, v2, v3
	global_store_dwordx4 v[248:249], v[4:7], off offset:256
	s_waitcnt vmcnt(24)
	s_waitcnt lgkmcnt(0)
	s_barrier
; #define PG8_STAGE(bufoff, gbase, voff) do { _Pragma("unroll") for (int _i = 0; _i < 2; ++_i) \
;         __builtin_amdgcn_global_load_lds((const unsigned*)((const char*)(gbase) + (voff)[_i]), (PG8_LAS unsigned*)(lds + (bufoff) + ldsw + _i * 8192), 16, 0, 0); } while (0)
; #define PG8_LDA(dst, b, h) do { _Pragma("unroll") for (int m = 0; m < 4; ++m) _Pragma("unroll") for (int k = 0; k < 2; ++k) dst[m][k] = *(const PG8_LAS bf16x8*)(lds + PG8_SA(b, h) + aoff + m * 2048 + k * 1024); } while (0)
; #define PG8_LDB(dst, b, h) do { _Pragma("unroll") for (int n = 0; n < 2; ++n) _Pragma("unroll") for (int k = 0; k < 2; ++k) dst[n][k] = *(const PG8_LAS bf16x8*)(lds + PG8_SB(b, h) + boff + n * 2048 + k * 1024); } while (0)
; #define PG8_MMA(ai, bj, At, Bt) do { __builtin_amdgcn_s_setprio(1); _Pragma("unroll") for (int m = 0; m < 4; ++m) _Pragma("unroll") for (int n = 0; n < 2; ++n) _Pragma("unroll") for (int k = 0; k < 2; ++k) \
;         acc[ai][bj][m][n] = __builtin_amdgcn_mfma_f32_16x16x32_bf16(Bt[n][k], At[m][k], acc[ai][bj][m][n], 0, 0, 0); __builtin_amdgcn_s_setprio(0); } while (0)
; #define PG8_WAIT_V(n) asm volatile("s_waitcnt vmcnt(" #n ")" ::: "memory")
; #define PG8_WAIT_L(n) asm volatile("s_waitcnt lgkmcnt(" #n ")" ::: "memory")
; #define PG8_BAR __builtin_amdgcn_s_barrier()
; #define PG8_SCHED __builtin_amdgcn_sched_barrier(0)
; template <class Epi, class Sched, bool ALIGN_EPI = false, bool SP2 = false, bool KHOOK = false>
; __device__ __forceinline__ void gemm_phase(PG8_LAS unsigned char* lds, const Gemm g, const Sched& S, const Epi& E, const int tid_in) {
;     ...
;             PG8_WAIT_V(8); PG8_WAIT_L(0); PG8_BAR; PG8_MMA(1, 0, At, B0); PG8_MMA(1, 1, At, B1); PG8_BAR; PG8_SCHED;
;             PG8_LDB(B0, 1, 0); PG8_LDB(B1, 1, 1); PG8_SCHED; PG8_LDA(At, 1, 0); PG8_STAGE(PG8_SA(0, 1), a2 + hstep, voffA);
;             PG8_WAIT_V(8); PG8_WAIT_L(0); PG8_BAR; PG8_MMA(0, 0, At, B0); PG8_MMA(0, 1, At, B1); PG8_BAR; PG8_SCHED;
	s_setprio 1
	s_waitcnt lgkmcnt(0)
	v_mfma_f32_16x16x32_bf16 v[62:65], v[144:147], v[176:179], 0
	v_mfma_f32_16x16x32_bf16 v[58:61], v[152:155], v[176:179], 0
	v_mfma_f32_16x16x32_bf16 v[54:57], v[144:147], v[184:187], 0
	v_mfma_f32_16x16x32_bf16 v[50:53], v[152:155], v[184:187], 0
	v_mfma_f32_16x16x32_bf16 v[38:41], v[144:147], v[198:201], 0
	v_mfma_f32_16x16x32_bf16 v[34:37], v[152:155], v[198:201], 0
	v_mfma_f32_16x16x32_bf16 v[20:23], v[144:147], v[206:209], 0
	v_mfma_f32_16x16x32_bf16 v[16:19], v[152:155], v[206:209], 0
	v_mfma_f32_16x16x32_bf16 v[62:65], v[148:151], v[180:183], v[62:65]
	v_mfma_f32_16x16x32_bf16 v[58:61], v[156:159], v[180:183], v[58:61]
	v_mfma_f32_16x16x32_bf16 v[54:57], v[148:151], v[188:191], v[54:57]
	v_mfma_f32_16x16x32_bf16 v[50:53], v[156:159], v[188:191], v[50:53]
	v_mfma_f32_16x16x32_bf16 v[38:41], v[148:151], v[202:205], v[38:41]
	v_mfma_f32_16x16x32_bf16 v[34:37], v[156:159], v[202:205], v[34:37]
	v_mfma_f32_16x16x32_bf16 v[20:23], v[148:151], v[210:213], v[20:23]
	v_mfma_f32_16x16x32_bf16 v[16:19], v[156:159], v[210:213], v[16:19]
	s_setprio 0
	s_setprio 1
	v_mfma_f32_16x16x32_bf16 v[46:49], v[160:163], v[176:179], 0
	v_mfma_f32_16x16x32_bf16 v[42:45], v[168:171], v[176:179], 0
	v_mfma_f32_16x16x32_bf16 v[28:31], v[160:163], v[184:187], 0
	v_mfma_f32_16x16x32_bf16 v[24:27], v[168:171], v[184:187], 0
	v_mfma_f32_16x16x32_bf16 v[12:15], v[160:163], v[198:201], 0
	v_mfma_f32_16x16x32_bf16 v[8:11], v[168:171], v[198:201], 0
	v_mfma_f32_16x16x32_bf16 v[4:7], v[160:163], v[206:209], 0
	v_mfma_f32_16x16x32_bf16 v[0:3], v[168:171], v[206:209], 0
	v_mfma_f32_16x16x32_bf16 v[46:49], v[164:167], v[180:183], v[46:49]
	v_mfma_f32_16x16x32_bf16 v[42:45], v[172:175], v[180:183], v[42:45]
	v_mfma_f32_16x16x32_bf16 v[28:31], v[164:167], v[188:191], v[28:31]
	v_mfma_f32_16x16x32_bf16 v[24:27], v[172:175], v[188:191], v[24:27]
	v_mfma_f32_16x16x32_bf16 v[12:15], v[164:167], v[202:205], v[12:15]
	v_mfma_f32_16x16x32_bf16 v[8:11], v[172:175], v[202:205], v[8:11]
	v_mfma_f32_16x16x32_bf16 v[4:7], v[164:167], v[210:213], v[4:7]
	v_mfma_f32_16x16x32_bf16 v[0:3], v[172:175], v[210:213], v[0:3]
	s_setprio 0
	s_barrier
	s_add_i32 s45, 0, 0x18000
	s_add_i32 s50, 0, 0x1c000
	v_add_u32_e32 v156, s45, v141
	v_add_u32_e32 v172, s50, v141
	ds_read_b128 v[144:147], v156
	ds_read_b128 v[148:151], v156 offset:1024
	ds_read_b128 v[152:155], v156 offset:2048
	ds_read_b128 v[156:159], v156 offset:3072
	ds_read_b128 v[160:163], v172
	ds_read_b128 v[164:167], v172 offset:1024
	ds_read_b128 v[168:171], v172 offset:2048
	ds_read_b128 v[172:175], v172 offset:3072
	s_add_u32 s46, s56, 0x80000
	s_addc_u32 s47, s57, 0
	s_mov_b32 m0, s25
	v_lshl_add_u64 v[220:221], s[46:47], 0, v[130:131]
	ds_read_b128 v[176:179], v143 offset:32768
	ds_read_b128 v[180:183], v143 offset:33792
	ds_read_b128 v[184:187], v143 offset:34816
	ds_read_b128 v[188:191], v143 offset:35840
	ds_read_b128 v[198:201], v143 offset:36864
	ds_read_b128 v[202:205], v143 offset:37888
	ds_read_b128 v[206:209], v143 offset:38912
	ds_read_b128 v[210:213], v143 offset:39936
	global_load_lds_dwordx4 v[220:221], off
	v_lshl_add_u64 v[220:221], s[46:47], 0, v[132:133]
	s_mov_b32 m0, s38
	s_nop 0
	global_load_lds_dwordx4 v[220:221], off
	s_waitcnt vmcnt(16)
	s_waitcnt lgkmcnt(0)
	s_barrier
	s_setprio 1
	s_waitcnt lgkmcnt(0)
	v_mfma_f32_16x16x32_bf16 v[126:129], v[144:147], v[176:179], v[126:129]
	v_mfma_f32_16x16x32_bf16 v[122:125], v[152:155], v[176:179], v[122:125]
	v_mfma_f32_16x16x32_bf16 v[118:121], v[144:147], v[184:187], v[118:121]
	v_mfma_f32_16x16x32_bf16 v[114:117], v[152:155], v[184:187], v[114:117]
	v_mfma_f32_16x16x32_bf16 v[102:105], v[144:147], v[198:201], v[102:105]
	v_mfma_f32_16x16x32_bf16 v[98:101], v[152:155], v[198:201], v[98:101]
	v_mfma_f32_16x16x32_bf16 v[86:89], v[144:147], v[206:209], v[86:89]
	v_mfma_f32_16x16x32_bf16 v[82:85], v[152:155], v[206:209], v[82:85]
	v_mfma_f32_16x16x32_bf16 v[126:129], v[148:151], v[180:183], v[126:129]
	v_mfma_f32_16x16x32_bf16 v[122:125], v[156:159], v[180:183], v[122:125]
	v_mfma_f32_16x16x32_bf16 v[118:121], v[148:151], v[188:191], v[118:121]
	v_mfma_f32_16x16x32_bf16 v[114:117], v[156:159], v[188:191], v[114:117]
	v_mfma_f32_16x16x32_bf16 v[102:105], v[148:151], v[202:205], v[102:105]
	v_mfma_f32_16x16x32_bf16 v[98:101], v[156:159], v[202:205], v[98:101]
	v_mfma_f32_16x16x32_bf16 v[86:89], v[148:151], v[210:213], v[86:89]
	v_mfma_f32_16x16x32_bf16 v[82:85], v[156:159], v[210:213], v[82:85]
	s_setprio 0
	s_setprio 1
	v_mfma_f32_16x16x32_bf16 v[110:113], v[160:163], v[176:179], v[110:113]
	v_mfma_f32_16x16x32_bf16 v[106:109], v[168:171], v[176:179], v[106:109]
	v_mfma_f32_16x16x32_bf16 v[94:97], v[160:163], v[184:187], v[94:97]
	v_mfma_f32_16x16x32_bf16 v[90:93], v[168:171], v[184:187], v[90:93]
	v_mfma_f32_16x16x32_bf16 v[78:81], v[160:163], v[198:201], v[78:81]
	v_mfma_f32_16x16x32_bf16 v[74:77], v[168:171], v[198:201], v[74:77]
	v_mfma_f32_16x16x32_bf16 v[70:73], v[160:163], v[206:209], v[70:73]
	v_mfma_f32_16x16x32_bf16 v[66:69], v[168:171], v[206:209], v[66:69]
	v_mfma_f32_16x16x32_bf16 v[110:113], v[164:167], v[180:183], v[110:113]
	v_mfma_f32_16x16x32_bf16 v[106:109], v[172:175], v[180:183], v[106:109]
	v_mfma_f32_16x16x32_bf16 v[94:97], v[164:167], v[188:191], v[94:97]
	v_mfma_f32_16x16x32_bf16 v[90:93], v[172:175], v[188:191], v[90:93]
	v_mfma_f32_16x16x32_bf16 v[78:81], v[164:167], v[202:205], v[78:81]
	v_mfma_f32_16x16x32_bf16 v[74:77], v[172:175], v[202:205], v[74:77]
	v_mfma_f32_16x16x32_bf16 v[70:73], v[164:167], v[210:213], v[70:73]
	v_mfma_f32_16x16x32_bf16 v[66:69], v[172:175], v[210:213], v[66:69]
	s_setprio 0
	s_barrier
; #define PG8_STAGE(bufoff, gbase, voff) do { _Pragma("unroll") for (int _i = 0; _i < 2; ++_i) \
;         __builtin_amdgcn_global_load_lds((const unsigned*)((const char*)(gbase) + (voff)[_i]), (PG8_LAS unsigned*)(lds + (bufoff) + ldsw + _i * 8192), 16, 0, 0); } while (0)
; #define PG8_LDA(dst, b, h) do { _Pragma("unroll") for (int m = 0; m < 4; ++m) _Pragma("unroll") for (int k = 0; k < 2; ++k) dst[m][k] = *(const PG8_LAS bf16x8*)(lds + PG8_SA(b, h) + aoff + m * 2048 + k * 1024); } while (0)
; #define PG8_MMA(ai, bj, At, Bt) do { __builtin_amdgcn_s_setprio(1); _Pragma("unroll") for (int m = 0; m < 4; ++m) _Pragma("unroll") for (int n = 0; n < 2; ++n) _Pragma("unroll") for (int k = 0; k < 2; ++k) \
;         acc[ai][bj][m][n] = __builtin_amdgcn_mfma_f32_16x16x32_bf16(Bt[n][k], At[m][k], acc[ai][bj][m][n], 0, 0, 0); __builtin_amdgcn_s_setprio(0); } while (0)
; #define PG8_WAIT_V(n) asm volatile("s_waitcnt vmcnt(" #n ")" ::: "memory")
; #define PG8_WAIT_L(n) asm volatile("s_waitcnt lgkmcnt(" #n ")" ::: "memory")
; #define PG8_BAR __builtin_amdgcn_s_barrier()
; #define PG8_SCHED __builtin_amdgcn_sched_barrier(0)
; template <class Epi, class Sched, bool ALIGN_EPI = false, bool SP2 = false, bool KHOOK = false>
; __device__ __forceinline__ void gemm_phase(PG8_LAS unsigned char* lds, const Gemm g, const Sched& S, const Epi& E, const int tid_in) {
;     ...
;             PG8_LDA(At, 1, 1); PG8_STAGE(PG8_SB(1, 0), b3, voffB); PG8_STAGE(PG8_SB(1, 1), b3 + hstep, voffB); PG8_STAGE(PG8_SA(1, 0), a3, voffA);
;             PG8_WAIT_V(8); PG8_WAIT_L(0); PG8_BAR; PG8_MMA(1, 0, At, B0); PG8_MMA(1, 1, At, B1); PG8_BAR; PG8_SCHED;
	s_add_i32 s45, s45, s37
	v_lshl_add_u64 v[192:193], v[192:193], 0, s[90:91]
	s_mov_b32 m0, s45
	ds_read_b128 v[176:179], v143 offset:49152
	ds_read_b128 v[180:183], v143 offset:50176
	ds_read_b128 v[184:187], v143 offset:51200
	ds_read_b128 v[188:191], v143 offset:52224
	ds_read_b128 v[198:201], v143 offset:53248
	ds_read_b128 v[202:205], v143 offset:54272
	ds_read_b128 v[206:209], v143 offset:55296
	ds_read_b128 v[210:213], v143 offset:56320
	global_load_lds_dwordx4 v[192:193], off
	s_add_i32 m0, s45, 0x2000
	s_add_u32 s46, s52, 0x80080
	v_lshl_add_u64 v[192:193], v[214:215], 0, s[90:91]
	s_addc_u32 s47, s53, 0
	s_add_i32 s45, s50, s37
	global_load_lds_dwordx4 v[192:193], off
	v_lshl_add_u64 v[192:193], s[46:47], 0, v[32:33]
	s_mov_b32 m0, s45
	s_nop 0
	global_load_lds_dwordx4 v[192:193], off
	v_lshl_add_u64 v[192:193], s[46:47], 0, v[134:135]
	s_add_i32 m0, s45, 0x2000
	s_nop 0
	global_load_lds_dwordx4 v[192:193], off
	v_lshl_add_u64 v[192:193], v[216:217], 0, s[90:91]
	s_mov_b32 m0, s39
	s_nop 0
	global_load_lds_dwordx4 v[192:193], off
	v_lshl_add_u64 v[192:193], v[218:219], 0, s[90:91]
	s_mov_b32 m0, s40
	s_nop 0
	global_load_lds_dwordx4 v[192:193], off
	s_waitcnt vmcnt(12)
	s_waitcnt lgkmcnt(0)
	s_barrier
	s_setprio 1
	s_waitcnt lgkmcnt(0)
	v_mfma_f32_16x16x32_bf16 v[62:65], v[144:147], v[176:179], v[62:65]
	v_mfma_f32_16x16x32_bf16 v[58:61], v[152:155], v[176:179], v[58:61]
	v_mfma_f32_16x16x32_bf16 v[54:57], v[144:147], v[184:187], v[54:57]
	v_mfma_f32_16x16x32_bf16 v[50:53], v[152:155], v[184:187], v[50:53]
	v_mfma_f32_16x16x32_bf16 v[38:41], v[144:147], v[198:201], v[38:41]
	v_mfma_f32_16x16x32_bf16 v[34:37], v[152:155], v[198:201], v[34:37]
	v_mfma_f32_16x16x32_bf16 v[20:23], v[144:147], v[206:209], v[20:23]
	v_mfma_f32_16x16x32_bf16 v[16:19], v[152:155], v[206:209], v[16:19]
	v_mfma_f32_16x16x32_bf16 v[62:65], v[148:151], v[180:183], v[62:65]
	v_mfma_f32_16x16x32_bf16 v[58:61], v[156:159], v[180:183], v[58:61]
	v_mfma_f32_16x16x32_bf16 v[54:57], v[148:151], v[188:191], v[54:57]
	v_mfma_f32_16x16x32_bf16 v[50:53], v[156:159], v[188:191], v[50:53]
	v_mfma_f32_16x16x32_bf16 v[38:41], v[148:151], v[202:205], v[38:41]
	v_mfma_f32_16x16x32_bf16 v[34:37], v[156:159], v[202:205], v[34:37]
	v_mfma_f32_16x16x32_bf16 v[20:23], v[148:151], v[210:213], v[20:23]
	v_mfma_f32_16x16x32_bf16 v[16:19], v[156:159], v[210:213], v[16:19]
	s_setprio 0
	s_setprio 1
	v_mfma_f32_16x16x32_bf16 v[46:49], v[160:163], v[176:179], v[46:49]
	v_mfma_f32_16x16x32_bf16 v[42:45], v[168:171], v[176:179], v[42:45]
	v_mfma_f32_16x16x32_bf16 v[28:31], v[160:163], v[184:187], v[28:31]
	v_mfma_f32_16x16x32_bf16 v[24:27], v[168:171], v[184:187], v[24:27]
	v_mfma_f32_16x16x32_bf16 v[12:15], v[160:163], v[198:201], v[12:15]
	v_mfma_f32_16x16x32_bf16 v[8:11], v[168:171], v[198:201], v[8:11]
	v_mfma_f32_16x16x32_bf16 v[4:7], v[160:163], v[206:209], v[4:7]
	v_mfma_f32_16x16x32_bf16 v[0:3], v[168:171], v[206:209], v[0:3]
	v_mfma_f32_16x16x32_bf16 v[46:49], v[164:167], v[180:183], v[46:49]
	v_mfma_f32_16x16x32_bf16 v[42:45], v[172:175], v[180:183], v[42:45]
	v_mfma_f32_16x16x32_bf16 v[28:31], v[164:167], v[188:191], v[28:31]
	v_mfma_f32_16x16x32_bf16 v[24:27], v[172:175], v[188:191], v[24:27]
	v_mfma_f32_16x16x32_bf16 v[12:15], v[164:167], v[202:205], v[12:15]
	v_mfma_f32_16x16x32_bf16 v[8:11], v[172:175], v[202:205], v[8:11]
	v_mfma_f32_16x16x32_bf16 v[4:7], v[164:167], v[210:213], v[4:7]
	v_mfma_f32_16x16x32_bf16 v[0:3], v[172:175], v[210:213], v[0:3]
	s_setprio 0
	s_barrier
	s_add_i32 s44, s44, 2
	s_add_u32 s48, s48, 0x100
	s_addc_u32 s49, s49, 0
	s_add_u32 s19, s19, 0x100
	s_addc_u32 s42, s42, 0
	s_cmp_gt_u32 s44, 29
